# expert U pass: h2 slice fetched by one cooperative load and redistributed through LDS (replaces 8 strided loads per pass)
# speedup vs baseline: 1.0120x; 1.0120x over previous
.Lex_chunk:
	s_movk_i32 s36, 0
	s_mul_i32 s37, s36, s5
	s_add_i32 s37, s37, s6
	s_min_u32 s37, s37, 0x3fff
	s_lshl_b32 s37, s37, 9
	s_add_u32 s82, s12, s37
	s_addc_u32 s83, s13, 0
	v_lshlrev_b32_e32 v219, 2, v228
	global_load_dword v96, v219, s[82:83]
	global_load_dword v97, v219, s[82:83] offset:256
	s_movk_i32 s36, 1
	s_mul_i32 s37, s36, s5
	s_add_i32 s37, s37, s6
	s_min_u32 s37, s37, 0x3fff
	s_lshl_b32 s37, s37, 9
	s_add_u32 s82, s12, s37
	s_addc_u32 s83, s13, 0
	v_lshlrev_b32_e32 v219, 2, v228
	global_load_dword v98, v219, s[82:83]
	global_load_dword v99, v219, s[82:83] offset:256
	s_movk_i32 s36, 2
	s_mul_i32 s37, s36, s5
	s_add_i32 s37, s37, s6
	s_min_u32 s37, s37, 0x3fff
	s_lshl_b32 s37, s37, 9
	s_add_u32 s82, s12, s37
	s_addc_u32 s83, s13, 0
	v_lshlrev_b32_e32 v219, 2, v228
	global_load_dword v100, v219, s[82:83]
	global_load_dword v101, v219, s[82:83] offset:256
	s_movk_i32 s36, 3
	s_mul_i32 s37, s36, s5
	s_add_i32 s37, s37, s6
	s_min_u32 s37, s37, 0x3fff
	s_lshl_b32 s37, s37, 9
	s_add_u32 s82, s12, s37
	s_addc_u32 s83, s13, 0
	v_lshlrev_b32_e32 v219, 2, v228
	global_load_dword v102, v219, s[82:83]
	global_load_dword v103, v219, s[82:83] offset:256
	s_movk_i32 s36, 4
	s_mul_i32 s37, s36, s5
	s_add_i32 s37, s37, s6
	s_min_u32 s37, s37, 0x3fff
	s_lshl_b32 s37, s37, 9
	s_add_u32 s82, s12, s37
	s_addc_u32 s83, s13, 0
	v_lshlrev_b32_e32 v219, 2, v228
	global_load_dword v104, v219, s[82:83]
	global_load_dword v105, v219, s[82:83] offset:256
	s_movk_i32 s36, 5
	s_mul_i32 s37, s36, s5
	s_add_i32 s37, s37, s6
	s_min_u32 s37, s37, 0x3fff
	s_lshl_b32 s37, s37, 9
	s_add_u32 s82, s12, s37
	s_addc_u32 s83, s13, 0
	v_lshlrev_b32_e32 v219, 2, v228
	global_load_dword v106, v219, s[82:83]
	global_load_dword v107, v219, s[82:83] offset:256
	s_movk_i32 s36, 6
	s_mul_i32 s37, s36, s5
	s_add_i32 s37, s37, s6
	s_min_u32 s37, s37, 0x3fff
	s_lshl_b32 s37, s37, 9
	s_add_u32 s82, s12, s37
	s_addc_u32 s83, s13, 0
	v_lshlrev_b32_e32 v219, 2, v228
	global_load_dword v108, v219, s[82:83]
	global_load_dword v109, v219, s[82:83] offset:256
	s_movk_i32 s36, 7
	s_mul_i32 s37, s36, s5
	s_add_i32 s37, s37, s6
	s_min_u32 s37, s37, 0x3fff
	s_lshl_b32 s37, s37, 9
	s_add_u32 s82, s12, s37
	s_addc_u32 s83, s13, 0
	v_lshlrev_b32_e32 v219, 2, v228
	global_load_dword v110, v219, s[82:83]
	global_load_dword v111, v219, s[82:83] offset:256
	s_waitcnt vmcnt(0)
	ds_write_b32 v230, v96 offset:0
	ds_write_b32 v230, v97 offset:256
	ds_write_b32 v230, v98 offset:512
	ds_write_b32 v230, v99 offset:768
	ds_write_b32 v230, v100 offset:1024
	ds_write_b32 v230, v101 offset:1280
	ds_write_b32 v230, v102 offset:1536
	ds_write_b32 v230, v103 offset:1792
	ds_write_b32 v230, v104 offset:2048
	ds_write_b32 v230, v105 offset:2304
	ds_write_b32 v230, v106 offset:2560
	ds_write_b32 v230, v107 offset:2816
	ds_write_b32 v230, v108 offset:3072
	ds_write_b32 v230, v109 offset:3328
	ds_write_b32 v230, v110 offset:3584
	ds_write_b32 v230, v111 offset:3840
	s_waitcnt lgkmcnt(0)
	v_lshrrev_b32_e32 v212, 3, v228
	v_lshl_add_u32 v234, v212, 9, v224
	s_lshr_b32 s34, s64, 13
	s_lshl_b32 s34, s34, 9
	s_add_i32 s34, s34, 0x10010
	v_lshl_add_u32 v235, v228, 3, s34
	v_add_u32_e32 v248, s34, v224
	s_mov_b32 s8, 0
	s_mov_b32 s7, 0
	s_mov_b32 s54, 0
	s_mov_b32 s53, 0
	s_mul_i32 s55, s53, s5
	s_add_i32 s55, s55, s6
	s_min_u32 s55, s55, 0x3fff
	s_and_b32 s34, s54, 7
	s_mul_i32 s34, s34, 0x300000
	s_cmp_lt_u32 s54, 8
	s_cselect_b32 s30, s16, s18
	s_cselect_b32 s31, s17, s19
	s_add_u32 s30, s30, s34
	s_addc_u32 s31, s31, 0
	s_and_b32 s34, s54, 7
	s_lshl_b32 s34, s34, 6
	s_lshl_b32 s35, s55, 12
	s_add_u32 s34, s34, s35
	s_add_u32 s32, s10, s34
	s_addc_u32 s33, s11, 0
	s_lshl_b32 s34, s53, 9
	v_add_u32_e32 v216, s34, v223
	ds_read_b128 v[80:83], v216 offset:0
	ds_read_b128 v[84:87], v216 offset:16
	ds_read_b128 v[88:91], v216 offset:32
	ds_read_b128 v[92:95], v216 offset:48
	s_waitcnt lgkmcnt(0)
	global_load_dwordx2 v[236:237], v234, s[32:33]
	v_mad_u32_u24 v217, v80, s52, v220
	v_add_u32_e32 v218, v217, v221
	global_load_dwordx4 v[96:99], v217, s[30:31]
	global_load_dwordx2 v[100:101], v218, s[30:31]
	v_mad_u32_u24 v217, v81, s52, v220
	v_add_u32_e32 v218, v217, v221
	global_load_dwordx4 v[102:105], v217, s[30:31]
	global_load_dwordx2 v[106:107], v218, s[30:31]
	v_mad_u32_u24 v217, v82, s52, v220
	v_add_u32_e32 v218, v217, v221
	global_load_dwordx4 v[108:111], v217, s[30:31]
	global_load_dwordx2 v[112:113], v218, s[30:31]
	v_mad_u32_u24 v217, v83, s52, v220
	v_add_u32_e32 v218, v217, v221
	global_load_dwordx4 v[114:117], v217, s[30:31]
	global_load_dwordx2 v[118:119], v218, s[30:31]
	v_mad_u32_u24 v217, v84, s52, v220
	v_add_u32_e32 v218, v217, v221
	global_load_dwordx4 v[120:123], v217, s[30:31]
	global_load_dwordx2 v[124:125], v218, s[30:31]
	v_mad_u32_u24 v217, v85, s52, v220
	v_add_u32_e32 v218, v217, v221
	global_load_dwordx4 v[126:129], v217, s[30:31]
	global_load_dwordx2 v[130:131], v218, s[30:31]
	v_mad_u32_u24 v217, v86, s52, v220
	v_add_u32_e32 v218, v217, v221
	global_load_dwordx4 v[132:135], v217, s[30:31]
	global_load_dwordx2 v[136:137], v218, s[30:31]
	v_mad_u32_u24 v217, v87, s52, v220
	v_add_u32_e32 v218, v217, v221
	global_load_dwordx4 v[138:141], v217, s[30:31]
	global_load_dwordx2 v[142:143], v218, s[30:31]
	v_mad_u32_u24 v217, v88, s52, v220
	v_add_u32_e32 v218, v217, v221
	global_load_dwordx4 v[144:147], v217, s[30:31]
	global_load_dwordx2 v[148:149], v218, s[30:31]
	v_mad_u32_u24 v217, v89, s52, v220
	v_add_u32_e32 v218, v217, v221
	global_load_dwordx4 v[150:153], v217, s[30:31]
	global_load_dwordx2 v[154:155], v218, s[30:31]
	v_mad_u32_u24 v217, v90, s52, v220
	v_add_u32_e32 v218, v217, v221
	global_load_dwordx4 v[156:159], v217, s[30:31]
	global_load_dwordx2 v[160:161], v218, s[30:31]
	v_mad_u32_u24 v217, v91, s52, v220
	v_add_u32_e32 v218, v217, v221
	global_load_dwordx4 v[162:165], v217, s[30:31]
	global_load_dwordx2 v[166:167], v218, s[30:31]
	v_mad_u32_u24 v217, v92, s52, v220
	v_add_u32_e32 v218, v217, v221
	global_load_dwordx4 v[168:171], v217, s[30:31]
	global_load_dwordx2 v[172:173], v218, s[30:31]
	v_mad_u32_u24 v217, v93, s52, v220
	v_add_u32_e32 v218, v217, v221
	global_load_dwordx4 v[174:177], v217, s[30:31]
	global_load_dwordx2 v[178:179], v218, s[30:31]
	v_mad_u32_u24 v217, v94, s52, v220
	v_add_u32_e32 v218, v217, v221
	global_load_dwordx4 v[180:183], v217, s[30:31]
	global_load_dwordx2 v[184:185], v218, s[30:31]
	v_mad_u32_u24 v217, v95, s52, v220
	v_add_u32_e32 v218, v217, v221
	global_load_dwordx4 v[186:189], v217, s[30:31]
	global_load_dwordx2 v[190:191], v218, s[30:31]
	s_waitcnt vmcnt(32)
	ds_write_b64 v235, v[236:237]
	ds_read_b64 v[64:65], v248 offset:0
	ds_read_b64 v[66:67], v248 offset:64
	ds_read_b64 v[68:69], v248 offset:128
	ds_read_b64 v[70:71], v248 offset:192
	ds_read_b64 v[72:73], v248 offset:256
	ds_read_b64 v[74:75], v248 offset:320
	ds_read_b64 v[76:77], v248 offset:384
	ds_read_b64 v[78:79], v248 offset:448
	s_add_i32 s53, s7, 1
	s_mov_b32 s54, s8
	s_cmp_eq_u32 s53, 8
	s_cselect_b32 s53, 0, s53
	s_cselect_b32 s34, 1, 0
	s_add_i32 s54, s54, s34
	s_mul_i32 s55, s53, s5
	s_add_i32 s55, s55, s6
	s_min_u32 s55, s55, 0x3fff
	s_and_b32 s34, s54, 7
	s_mul_i32 s34, s34, 0x300000
	s_cmp_lt_u32 s54, 8
	s_cselect_b32 s30, s16, s18
	s_cselect_b32 s31, s17, s19
	s_add_u32 s30, s30, s34
	s_addc_u32 s31, s31, 0
	s_and_b32 s34, s54, 7
	s_lshl_b32 s34, s34, 6
	s_lshl_b32 s35, s55, 12
	s_add_u32 s34, s34, s35
	s_add_u32 s32, s10, s34
	s_addc_u32 s33, s11, 0
	s_lshl_b32 s34, s53, 9
	v_add_u32_e32 v216, s34, v223
	ds_read_b128 v[80:83], v216 offset:0
	ds_read_b128 v[84:87], v216 offset:16
	ds_read_b128 v[88:91], v216 offset:32
	ds_read_b128 v[92:95], v216 offset:48
.Lex_uloop:
	s_waitcnt lgkmcnt(0)
	v_lshlrev_b32_e32 v32, 16, v64
	v_and_b32_e32 v33, 0xffff0000, v64
	v_lshlrev_b32_e32 v34, 16, v65
	v_and_b32_e32 v35, 0xffff0000, v65
	v_lshlrev_b32_e32 v36, 16, v66
	v_and_b32_e32 v37, 0xffff0000, v66
	v_lshlrev_b32_e32 v38, 16, v67
	v_and_b32_e32 v39, 0xffff0000, v67
	v_lshlrev_b32_e32 v40, 16, v68
	v_and_b32_e32 v41, 0xffff0000, v68
	v_lshlrev_b32_e32 v42, 16, v69
	v_and_b32_e32 v43, 0xffff0000, v69
	v_lshlrev_b32_e32 v44, 16, v70
	v_and_b32_e32 v45, 0xffff0000, v70
	v_lshlrev_b32_e32 v46, 16, v71
	v_and_b32_e32 v47, 0xffff0000, v71
	v_lshlrev_b32_e32 v48, 16, v72
	v_and_b32_e32 v49, 0xffff0000, v72
	v_lshlrev_b32_e32 v50, 16, v73
	v_and_b32_e32 v51, 0xffff0000, v73
	v_lshlrev_b32_e32 v52, 16, v74
	v_and_b32_e32 v53, 0xffff0000, v74
	v_lshlrev_b32_e32 v54, 16, v75
	v_and_b32_e32 v55, 0xffff0000, v75
	v_lshlrev_b32_e32 v56, 16, v76
	v_and_b32_e32 v57, 0xffff0000, v76
	v_lshlrev_b32_e32 v58, 16, v77
	v_and_b32_e32 v59, 0xffff0000, v77
	v_lshlrev_b32_e32 v60, 16, v78
	v_and_b32_e32 v61, 0xffff0000, v78
	v_lshlrev_b32_e32 v62, 16, v79
	v_and_b32_e32 v63, 0xffff0000, v79
	s_waitcnt lgkmcnt(0)
	s_waitcnt vmcnt(30)
	v_cvt_scalef32_pk32_f32_fp6 v[0:31], v[96:101], 1.0
	v_pk_mul_f32 v[208:209], v[0:1], v[32:33]
	v_pk_mul_f32 v[210:211], v[2:3], v[34:35]
	v_pk_fma_f32 v[208:209], v[4:5], v[36:37], v[208:209]
	v_pk_fma_f32 v[210:211], v[6:7], v[38:39], v[210:211]
	v_pk_fma_f32 v[208:209], v[8:9], v[40:41], v[208:209]
	v_pk_fma_f32 v[210:211], v[10:11], v[42:43], v[210:211]
	v_pk_fma_f32 v[208:209], v[12:13], v[44:45], v[208:209]
	v_pk_fma_f32 v[210:211], v[14:15], v[46:47], v[210:211]
	v_pk_fma_f32 v[208:209], v[16:17], v[48:49], v[208:209]
	v_pk_fma_f32 v[210:211], v[18:19], v[50:51], v[210:211]
	v_pk_fma_f32 v[208:209], v[20:21], v[52:53], v[208:209]
	v_pk_fma_f32 v[210:211], v[22:23], v[54:55], v[210:211]
	v_pk_fma_f32 v[208:209], v[24:25], v[56:57], v[208:209]
	v_pk_fma_f32 v[210:211], v[26:27], v[58:59], v[210:211]
	v_pk_fma_f32 v[208:209], v[28:29], v[60:61], v[208:209]
	v_pk_fma_f32 v[210:211], v[30:31], v[62:63], v[210:211]
	v_pk_add_f32 v[208:209], v[208:209], v[210:211]
	v_add_f32_e32 v192, v208, v209
	global_load_dwordx2 v[236:237], v234, s[32:33]
	v_mad_u32_u24 v217, v80, s52, v220
	v_add_u32_e32 v218, v217, v221
	global_load_dwordx4 v[96:99], v217, s[30:31]
	global_load_dwordx2 v[100:101], v218, s[30:31]
	s_waitcnt vmcnt(31)
	v_cvt_scalef32_pk32_f32_fp6 v[0:31], v[102:107], 1.0
	v_pk_mul_f32 v[208:209], v[0:1], v[32:33]
	v_pk_mul_f32 v[210:211], v[2:3], v[34:35]
	v_pk_fma_f32 v[208:209], v[4:5], v[36:37], v[208:209]
	v_pk_fma_f32 v[210:211], v[6:7], v[38:39], v[210:211]
	v_pk_fma_f32 v[208:209], v[8:9], v[40:41], v[208:209]
	v_pk_fma_f32 v[210:211], v[10:11], v[42:43], v[210:211]
	v_pk_fma_f32 v[208:209], v[12:13], v[44:45], v[208:209]
	v_pk_fma_f32 v[210:211], v[14:15], v[46:47], v[210:211]
	v_pk_fma_f32 v[208:209], v[16:17], v[48:49], v[208:209]
	v_pk_fma_f32 v[210:211], v[18:19], v[50:51], v[210:211]
	v_pk_fma_f32 v[208:209], v[20:21], v[52:53], v[208:209]
	v_pk_fma_f32 v[210:211], v[22:23], v[54:55], v[210:211]
	v_pk_fma_f32 v[208:209], v[24:25], v[56:57], v[208:209]
	v_pk_fma_f32 v[210:211], v[26:27], v[58:59], v[210:211]
	v_pk_fma_f32 v[208:209], v[28:29], v[60:61], v[208:209]
	v_pk_fma_f32 v[210:211], v[30:31], v[62:63], v[210:211]
	v_pk_add_f32 v[208:209], v[208:209], v[210:211]
	v_add_f32_e32 v193, v208, v209
	v_mad_u32_u24 v217, v81, s52, v220
	v_add_u32_e32 v218, v217, v221
	global_load_dwordx4 v[102:105], v217, s[30:31]
	global_load_dwordx2 v[106:107], v218, s[30:31]
	s_waitcnt vmcnt(31)
	v_cvt_scalef32_pk32_f32_fp6 v[0:31], v[108:113], 1.0
	v_pk_mul_f32 v[208:209], v[0:1], v[32:33]
	v_pk_mul_f32 v[210:211], v[2:3], v[34:35]
	v_pk_fma_f32 v[208:209], v[4:5], v[36:37], v[208:209]
	v_pk_fma_f32 v[210:211], v[6:7], v[38:39], v[210:211]
	v_pk_fma_f32 v[208:209], v[8:9], v[40:41], v[208:209]
	v_pk_fma_f32 v[210:211], v[10:11], v[42:43], v[210:211]
	v_pk_fma_f32 v[208:209], v[12:13], v[44:45], v[208:209]
	v_pk_fma_f32 v[210:211], v[14:15], v[46:47], v[210:211]
	v_pk_fma_f32 v[208:209], v[16:17], v[48:49], v[208:209]
	v_pk_fma_f32 v[210:211], v[18:19], v[50:51], v[210:211]
	v_pk_fma_f32 v[208:209], v[20:21], v[52:53], v[208:209]
	v_pk_fma_f32 v[210:211], v[22:23], v[54:55], v[210:211]
	v_pk_fma_f32 v[208:209], v[24:25], v[56:57], v[208:209]
	v_pk_fma_f32 v[210:211], v[26:27], v[58:59], v[210:211]
	v_pk_fma_f32 v[208:209], v[28:29], v[60:61], v[208:209]
	v_pk_fma_f32 v[210:211], v[30:31], v[62:63], v[210:211]
	v_pk_add_f32 v[208:209], v[208:209], v[210:211]
	v_add_f32_e32 v194, v208, v209
	v_mad_u32_u24 v217, v82, s52, v220
	v_add_u32_e32 v218, v217, v221
	global_load_dwordx4 v[108:111], v217, s[30:31]
	global_load_dwordx2 v[112:113], v218, s[30:31]
	s_waitcnt vmcnt(31)
	v_cvt_scalef32_pk32_f32_fp6 v[0:31], v[114:119], 1.0
	v_pk_mul_f32 v[208:209], v[0:1], v[32:33]
	v_pk_mul_f32 v[210:211], v[2:3], v[34:35]
	v_pk_fma_f32 v[208:209], v[4:5], v[36:37], v[208:209]
	v_pk_fma_f32 v[210:211], v[6:7], v[38:39], v[210:211]
	v_pk_fma_f32 v[208:209], v[8:9], v[40:41], v[208:209]
	v_pk_fma_f32 v[210:211], v[10:11], v[42:43], v[210:211]
	v_pk_fma_f32 v[208:209], v[12:13], v[44:45], v[208:209]
	v_pk_fma_f32 v[210:211], v[14:15], v[46:47], v[210:211]
	v_pk_fma_f32 v[208:209], v[16:17], v[48:49], v[208:209]
	v_pk_fma_f32 v[210:211], v[18:19], v[50:51], v[210:211]
	v_pk_fma_f32 v[208:209], v[20:21], v[52:53], v[208:209]
	v_pk_fma_f32 v[210:211], v[22:23], v[54:55], v[210:211]
	v_pk_fma_f32 v[208:209], v[24:25], v[56:57], v[208:209]
	v_pk_fma_f32 v[210:211], v[26:27], v[58:59], v[210:211]
	v_pk_fma_f32 v[208:209], v[28:29], v[60:61], v[208:209]
	v_pk_fma_f32 v[210:211], v[30:31], v[62:63], v[210:211]
	v_pk_add_f32 v[208:209], v[208:209], v[210:211]
	v_add_f32_e32 v195, v208, v209
	v_mad_u32_u24 v217, v83, s52, v220
	v_add_u32_e32 v218, v217, v221
	global_load_dwordx4 v[114:117], v217, s[30:31]
	global_load_dwordx2 v[118:119], v218, s[30:31]
	s_waitcnt vmcnt(31)
	v_cvt_scalef32_pk32_f32_fp6 v[0:31], v[120:125], 1.0
	v_pk_mul_f32 v[208:209], v[0:1], v[32:33]
	v_pk_mul_f32 v[210:211], v[2:3], v[34:35]
	v_pk_fma_f32 v[208:209], v[4:5], v[36:37], v[208:209]
	v_pk_fma_f32 v[210:211], v[6:7], v[38:39], v[210:211]
	v_pk_fma_f32 v[208:209], v[8:9], v[40:41], v[208:209]
	v_pk_fma_f32 v[210:211], v[10:11], v[42:43], v[210:211]
	v_pk_fma_f32 v[208:209], v[12:13], v[44:45], v[208:209]
	v_pk_fma_f32 v[210:211], v[14:15], v[46:47], v[210:211]
	v_pk_fma_f32 v[208:209], v[16:17], v[48:49], v[208:209]
	v_pk_fma_f32 v[210:211], v[18:19], v[50:51], v[210:211]
	v_pk_fma_f32 v[208:209], v[20:21], v[52:53], v[208:209]
	v_pk_fma_f32 v[210:211], v[22:23], v[54:55], v[210:211]
	v_pk_fma_f32 v[208:209], v[24:25], v[56:57], v[208:209]
	v_pk_fma_f32 v[210:211], v[26:27], v[58:59], v[210:211]
	v_pk_fma_f32 v[208:209], v[28:29], v[60:61], v[208:209]
	v_pk_fma_f32 v[210:211], v[30:31], v[62:63], v[210:211]
	v_pk_add_f32 v[208:209], v[208:209], v[210:211]
	v_add_f32_e32 v196, v208, v209
	v_mad_u32_u24 v217, v84, s52, v220
	v_add_u32_e32 v218, v217, v221
	global_load_dwordx4 v[120:123], v217, s[30:31]
	global_load_dwordx2 v[124:125], v218, s[30:31]
	s_waitcnt vmcnt(31)
	v_cvt_scalef32_pk32_f32_fp6 v[0:31], v[126:131], 1.0
	v_pk_mul_f32 v[208:209], v[0:1], v[32:33]
	v_pk_mul_f32 v[210:211], v[2:3], v[34:35]
	v_pk_fma_f32 v[208:209], v[4:5], v[36:37], v[208:209]
	v_pk_fma_f32 v[210:211], v[6:7], v[38:39], v[210:211]
	v_pk_fma_f32 v[208:209], v[8:9], v[40:41], v[208:209]
	v_pk_fma_f32 v[210:211], v[10:11], v[42:43], v[210:211]
	v_pk_fma_f32 v[208:209], v[12:13], v[44:45], v[208:209]
	v_pk_fma_f32 v[210:211], v[14:15], v[46:47], v[210:211]
	v_pk_fma_f32 v[208:209], v[16:17], v[48:49], v[208:209]
	v_pk_fma_f32 v[210:211], v[18:19], v[50:51], v[210:211]
	v_pk_fma_f32 v[208:209], v[20:21], v[52:53], v[208:209]
	v_pk_fma_f32 v[210:211], v[22:23], v[54:55], v[210:211]
	v_pk_fma_f32 v[208:209], v[24:25], v[56:57], v[208:209]
	v_pk_fma_f32 v[210:211], v[26:27], v[58:59], v[210:211]
	v_pk_fma_f32 v[208:209], v[28:29], v[60:61], v[208:209]
	v_pk_fma_f32 v[210:211], v[30:31], v[62:63], v[210:211]
	v_pk_add_f32 v[208:209], v[208:209], v[210:211]
	v_add_f32_e32 v197, v208, v209
	v_mad_u32_u24 v217, v85, s52, v220
	v_add_u32_e32 v218, v217, v221
	global_load_dwordx4 v[126:129], v217, s[30:31]
	global_load_dwordx2 v[130:131], v218, s[30:31]
	s_waitcnt vmcnt(31)
	v_cvt_scalef32_pk32_f32_fp6 v[0:31], v[132:137], 1.0
	v_pk_mul_f32 v[208:209], v[0:1], v[32:33]
	v_pk_mul_f32 v[210:211], v[2:3], v[34:35]
	v_pk_fma_f32 v[208:209], v[4:5], v[36:37], v[208:209]
	v_pk_fma_f32 v[210:211], v[6:7], v[38:39], v[210:211]
	v_pk_fma_f32 v[208:209], v[8:9], v[40:41], v[208:209]
	v_pk_fma_f32 v[210:211], v[10:11], v[42:43], v[210:211]
	v_pk_fma_f32 v[208:209], v[12:13], v[44:45], v[208:209]
	v_pk_fma_f32 v[210:211], v[14:15], v[46:47], v[210:211]
	v_pk_fma_f32 v[208:209], v[16:17], v[48:49], v[208:209]
	v_pk_fma_f32 v[210:211], v[18:19], v[50:51], v[210:211]
	v_pk_fma_f32 v[208:209], v[20:21], v[52:53], v[208:209]
	v_pk_fma_f32 v[210:211], v[22:23], v[54:55], v[210:211]
	v_pk_fma_f32 v[208:209], v[24:25], v[56:57], v[208:209]
	v_pk_fma_f32 v[210:211], v[26:27], v[58:59], v[210:211]
	v_pk_fma_f32 v[208:209], v[28:29], v[60:61], v[208:209]
	v_pk_fma_f32 v[210:211], v[30:31], v[62:63], v[210:211]
	v_pk_add_f32 v[208:209], v[208:209], v[210:211]
	v_add_f32_e32 v198, v208, v209
	v_mad_u32_u24 v217, v86, s52, v220
	v_add_u32_e32 v218, v217, v221
	global_load_dwordx4 v[132:135], v217, s[30:31]
	global_load_dwordx2 v[136:137], v218, s[30:31]
	s_waitcnt vmcnt(31)
	v_cvt_scalef32_pk32_f32_fp6 v[0:31], v[138:143], 1.0
	v_pk_mul_f32 v[208:209], v[0:1], v[32:33]
	v_pk_mul_f32 v[210:211], v[2:3], v[34:35]
	v_pk_fma_f32 v[208:209], v[4:5], v[36:37], v[208:209]
	v_pk_fma_f32 v[210:211], v[6:7], v[38:39], v[210:211]
	v_pk_fma_f32 v[208:209], v[8:9], v[40:41], v[208:209]
	v_pk_fma_f32 v[210:211], v[10:11], v[42:43], v[210:211]
	v_pk_fma_f32 v[208:209], v[12:13], v[44:45], v[208:209]
	v_pk_fma_f32 v[210:211], v[14:15], v[46:47], v[210:211]
	v_pk_fma_f32 v[208:209], v[16:17], v[48:49], v[208:209]
	v_pk_fma_f32 v[210:211], v[18:19], v[50:51], v[210:211]
	v_pk_fma_f32 v[208:209], v[20:21], v[52:53], v[208:209]
	v_pk_fma_f32 v[210:211], v[22:23], v[54:55], v[210:211]
	v_pk_fma_f32 v[208:209], v[24:25], v[56:57], v[208:209]
	v_pk_fma_f32 v[210:211], v[26:27], v[58:59], v[210:211]
	v_pk_fma_f32 v[208:209], v[28:29], v[60:61], v[208:209]
	v_pk_fma_f32 v[210:211], v[30:31], v[62:63], v[210:211]
	v_pk_add_f32 v[208:209], v[208:209], v[210:211]
	v_add_f32_e32 v199, v208, v209
	v_mad_u32_u24 v217, v87, s52, v220
	v_add_u32_e32 v218, v217, v221
	global_load_dwordx4 v[138:141], v217, s[30:31]
	global_load_dwordx2 v[142:143], v218, s[30:31]
	s_waitcnt vmcnt(31)
	v_cvt_scalef32_pk32_f32_fp6 v[0:31], v[144:149], 1.0
	v_pk_mul_f32 v[208:209], v[0:1], v[32:33]
	v_pk_mul_f32 v[210:211], v[2:3], v[34:35]
	v_pk_fma_f32 v[208:209], v[4:5], v[36:37], v[208:209]
	v_pk_fma_f32 v[210:211], v[6:7], v[38:39], v[210:211]
	v_pk_fma_f32 v[208:209], v[8:9], v[40:41], v[208:209]
	v_pk_fma_f32 v[210:211], v[10:11], v[42:43], v[210:211]
	v_pk_fma_f32 v[208:209], v[12:13], v[44:45], v[208:209]
	v_pk_fma_f32 v[210:211], v[14:15], v[46:47], v[210:211]
	v_pk_fma_f32 v[208:209], v[16:17], v[48:49], v[208:209]
	v_pk_fma_f32 v[210:211], v[18:19], v[50:51], v[210:211]
	v_pk_fma_f32 v[208:209], v[20:21], v[52:53], v[208:209]
	v_pk_fma_f32 v[210:211], v[22:23], v[54:55], v[210:211]
	v_pk_fma_f32 v[208:209], v[24:25], v[56:57], v[208:209]
	v_pk_fma_f32 v[210:211], v[26:27], v[58:59], v[210:211]
	v_pk_fma_f32 v[208:209], v[28:29], v[60:61], v[208:209]
	v_pk_fma_f32 v[210:211], v[30:31], v[62:63], v[210:211]
	v_pk_add_f32 v[208:209], v[208:209], v[210:211]
	v_add_f32_e32 v200, v208, v209
	s_waitcnt vmcnt(16)
	ds_write_b64 v235, v[236:237]
	ds_read_b64 v[64:65], v248 offset:0
	ds_read_b64 v[66:67], v248 offset:64
	ds_read_b64 v[68:69], v248 offset:128
	ds_read_b64 v[70:71], v248 offset:192
	ds_read_b64 v[72:73], v248 offset:256
	ds_read_b64 v[74:75], v248 offset:320
	ds_read_b64 v[76:77], v248 offset:384
	ds_read_b64 v[78:79], v248 offset:448
	v_mad_u32_u24 v217, v88, s52, v220
	v_add_u32_e32 v218, v217, v221
	global_load_dwordx4 v[144:147], v217, s[30:31]
	global_load_dwordx2 v[148:149], v218, s[30:31]
	v_cvt_scalef32_pk32_f32_fp6 v[0:31], v[150:155], 1.0
	v_pk_mul_f32 v[208:209], v[0:1], v[32:33]
	v_pk_mul_f32 v[210:211], v[2:3], v[34:35]
	v_pk_fma_f32 v[208:209], v[4:5], v[36:37], v[208:209]
	v_pk_fma_f32 v[210:211], v[6:7], v[38:39], v[210:211]
	v_pk_fma_f32 v[208:209], v[8:9], v[40:41], v[208:209]
	v_pk_fma_f32 v[210:211], v[10:11], v[42:43], v[210:211]
	v_pk_fma_f32 v[208:209], v[12:13], v[44:45], v[208:209]
	v_pk_fma_f32 v[210:211], v[14:15], v[46:47], v[210:211]
	v_pk_fma_f32 v[208:209], v[16:17], v[48:49], v[208:209]
	v_pk_fma_f32 v[210:211], v[18:19], v[50:51], v[210:211]
	v_pk_fma_f32 v[208:209], v[20:21], v[52:53], v[208:209]
	v_pk_fma_f32 v[210:211], v[22:23], v[54:55], v[210:211]
	v_pk_fma_f32 v[208:209], v[24:25], v[56:57], v[208:209]
	v_pk_fma_f32 v[210:211], v[26:27], v[58:59], v[210:211]
	v_pk_fma_f32 v[208:209], v[28:29], v[60:61], v[208:209]
	v_pk_fma_f32 v[210:211], v[30:31], v[62:63], v[210:211]
	v_pk_add_f32 v[208:209], v[208:209], v[210:211]
	v_add_f32_e32 v201, v208, v209
	v_mad_u32_u24 v217, v89, s52, v220
	v_add_u32_e32 v218, v217, v221
	global_load_dwordx4 v[150:153], v217, s[30:31]
	global_load_dwordx2 v[154:155], v218, s[30:31]
	v_cvt_scalef32_pk32_f32_fp6 v[0:31], v[156:161], 1.0
	v_pk_mul_f32 v[208:209], v[0:1], v[32:33]
	v_pk_mul_f32 v[210:211], v[2:3], v[34:35]
	v_pk_fma_f32 v[208:209], v[4:5], v[36:37], v[208:209]
	v_pk_fma_f32 v[210:211], v[6:7], v[38:39], v[210:211]
	v_pk_fma_f32 v[208:209], v[8:9], v[40:41], v[208:209]
	v_pk_fma_f32 v[210:211], v[10:11], v[42:43], v[210:211]
	v_pk_fma_f32 v[208:209], v[12:13], v[44:45], v[208:209]
	v_pk_fma_f32 v[210:211], v[14:15], v[46:47], v[210:211]
	v_pk_fma_f32 v[208:209], v[16:17], v[48:49], v[208:209]
	v_pk_fma_f32 v[210:211], v[18:19], v[50:51], v[210:211]
	v_pk_fma_f32 v[208:209], v[20:21], v[52:53], v[208:209]
	v_pk_fma_f32 v[210:211], v[22:23], v[54:55], v[210:211]
	v_pk_fma_f32 v[208:209], v[24:25], v[56:57], v[208:209]
	v_pk_fma_f32 v[210:211], v[26:27], v[58:59], v[210:211]
	v_pk_fma_f32 v[208:209], v[28:29], v[60:61], v[208:209]
	v_pk_fma_f32 v[210:211], v[30:31], v[62:63], v[210:211]
	v_pk_add_f32 v[208:209], v[208:209], v[210:211]
	v_add_f32_e32 v202, v208, v209
	v_mad_u32_u24 v217, v90, s52, v220
	v_add_u32_e32 v218, v217, v221
	global_load_dwordx4 v[156:159], v217, s[30:31]
	global_load_dwordx2 v[160:161], v218, s[30:31]
	v_cvt_scalef32_pk32_f32_fp6 v[0:31], v[162:167], 1.0
	v_pk_mul_f32 v[208:209], v[0:1], v[32:33]
	v_pk_mul_f32 v[210:211], v[2:3], v[34:35]
	v_pk_fma_f32 v[208:209], v[4:5], v[36:37], v[208:209]
	v_pk_fma_f32 v[210:211], v[6:7], v[38:39], v[210:211]
	v_pk_fma_f32 v[208:209], v[8:9], v[40:41], v[208:209]
	v_pk_fma_f32 v[210:211], v[10:11], v[42:43], v[210:211]
	v_pk_fma_f32 v[208:209], v[12:13], v[44:45], v[208:209]
	v_pk_fma_f32 v[210:211], v[14:15], v[46:47], v[210:211]
	v_pk_fma_f32 v[208:209], v[16:17], v[48:49], v[208:209]
	v_pk_fma_f32 v[210:211], v[18:19], v[50:51], v[210:211]
	v_pk_fma_f32 v[208:209], v[20:21], v[52:53], v[208:209]
	v_pk_fma_f32 v[210:211], v[22:23], v[54:55], v[210:211]
	v_pk_fma_f32 v[208:209], v[24:25], v[56:57], v[208:209]
	v_pk_fma_f32 v[210:211], v[26:27], v[58:59], v[210:211]
	v_pk_fma_f32 v[208:209], v[28:29], v[60:61], v[208:209]
	v_pk_fma_f32 v[210:211], v[30:31], v[62:63], v[210:211]
	v_pk_add_f32 v[208:209], v[208:209], v[210:211]
	v_add_f32_e32 v203, v208, v209
	v_mad_u32_u24 v217, v91, s52, v220
	v_add_u32_e32 v218, v217, v221
	global_load_dwordx4 v[162:165], v217, s[30:31]
	global_load_dwordx2 v[166:167], v218, s[30:31]
	v_cvt_scalef32_pk32_f32_fp6 v[0:31], v[168:173], 1.0
	v_pk_mul_f32 v[208:209], v[0:1], v[32:33]
	v_pk_mul_f32 v[210:211], v[2:3], v[34:35]
	v_pk_fma_f32 v[208:209], v[4:5], v[36:37], v[208:209]
	v_pk_fma_f32 v[210:211], v[6:7], v[38:39], v[210:211]
	v_pk_fma_f32 v[208:209], v[8:9], v[40:41], v[208:209]
	v_pk_fma_f32 v[210:211], v[10:11], v[42:43], v[210:211]
	v_pk_fma_f32 v[208:209], v[12:13], v[44:45], v[208:209]
	v_pk_fma_f32 v[210:211], v[14:15], v[46:47], v[210:211]
	v_pk_fma_f32 v[208:209], v[16:17], v[48:49], v[208:209]
	v_pk_fma_f32 v[210:211], v[18:19], v[50:51], v[210:211]
	v_pk_fma_f32 v[208:209], v[20:21], v[52:53], v[208:209]
	v_pk_fma_f32 v[210:211], v[22:23], v[54:55], v[210:211]
	v_pk_fma_f32 v[208:209], v[24:25], v[56:57], v[208:209]
	v_pk_fma_f32 v[210:211], v[26:27], v[58:59], v[210:211]
	v_pk_fma_f32 v[208:209], v[28:29], v[60:61], v[208:209]
	v_pk_fma_f32 v[210:211], v[30:31], v[62:63], v[210:211]
	v_pk_add_f32 v[208:209], v[208:209], v[210:211]
	v_add_f32_e32 v204, v208, v209
	v_mad_u32_u24 v217, v92, s52, v220
	v_add_u32_e32 v218, v217, v221
	global_load_dwordx4 v[168:171], v217, s[30:31]
	global_load_dwordx2 v[172:173], v218, s[30:31]
	v_cvt_scalef32_pk32_f32_fp6 v[0:31], v[174:179], 1.0
	v_pk_mul_f32 v[208:209], v[0:1], v[32:33]
	v_pk_mul_f32 v[210:211], v[2:3], v[34:35]
	v_pk_fma_f32 v[208:209], v[4:5], v[36:37], v[208:209]
	v_pk_fma_f32 v[210:211], v[6:7], v[38:39], v[210:211]
	v_pk_fma_f32 v[208:209], v[8:9], v[40:41], v[208:209]
	v_pk_fma_f32 v[210:211], v[10:11], v[42:43], v[210:211]
	v_pk_fma_f32 v[208:209], v[12:13], v[44:45], v[208:209]
	v_pk_fma_f32 v[210:211], v[14:15], v[46:47], v[210:211]
	v_pk_fma_f32 v[208:209], v[16:17], v[48:49], v[208:209]
	v_pk_fma_f32 v[210:211], v[18:19], v[50:51], v[210:211]
	v_pk_fma_f32 v[208:209], v[20:21], v[52:53], v[208:209]
	v_pk_fma_f32 v[210:211], v[22:23], v[54:55], v[210:211]
	v_pk_fma_f32 v[208:209], v[24:25], v[56:57], v[208:209]
	v_pk_fma_f32 v[210:211], v[26:27], v[58:59], v[210:211]
	v_pk_fma_f32 v[208:209], v[28:29], v[60:61], v[208:209]
	v_pk_fma_f32 v[210:211], v[30:31], v[62:63], v[210:211]
	v_pk_add_f32 v[208:209], v[208:209], v[210:211]
	v_add_f32_e32 v205, v208, v209
	v_mad_u32_u24 v217, v93, s52, v220
	v_add_u32_e32 v218, v217, v221
	global_load_dwordx4 v[174:177], v217, s[30:31]
	global_load_dwordx2 v[178:179], v218, s[30:31]
	v_cvt_scalef32_pk32_f32_fp6 v[0:31], v[180:185], 1.0
	v_pk_mul_f32 v[208:209], v[0:1], v[32:33]
	v_pk_mul_f32 v[210:211], v[2:3], v[34:35]
	v_pk_fma_f32 v[208:209], v[4:5], v[36:37], v[208:209]
	v_pk_fma_f32 v[210:211], v[6:7], v[38:39], v[210:211]
	v_pk_fma_f32 v[208:209], v[8:9], v[40:41], v[208:209]
	v_pk_fma_f32 v[210:211], v[10:11], v[42:43], v[210:211]
	v_pk_fma_f32 v[208:209], v[12:13], v[44:45], v[208:209]
	v_pk_fma_f32 v[210:211], v[14:15], v[46:47], v[210:211]
	v_pk_fma_f32 v[208:209], v[16:17], v[48:49], v[208:209]
	v_pk_fma_f32 v[210:211], v[18:19], v[50:51], v[210:211]
	v_pk_fma_f32 v[208:209], v[20:21], v[52:53], v[208:209]
	v_pk_fma_f32 v[210:211], v[22:23], v[54:55], v[210:211]
	v_pk_fma_f32 v[208:209], v[24:25], v[56:57], v[208:209]
	v_pk_fma_f32 v[210:211], v[26:27], v[58:59], v[210:211]
	v_pk_fma_f32 v[208:209], v[28:29], v[60:61], v[208:209]
	v_pk_fma_f32 v[210:211], v[30:31], v[62:63], v[210:211]
	v_pk_add_f32 v[208:209], v[208:209], v[210:211]
	v_add_f32_e32 v206, v208, v209
	v_mad_u32_u24 v217, v94, s52, v220
	v_add_u32_e32 v218, v217, v221
	global_load_dwordx4 v[180:183], v217, s[30:31]
	global_load_dwordx2 v[184:185], v218, s[30:31]
	v_cvt_scalef32_pk32_f32_fp6 v[0:31], v[186:191], 1.0
	v_pk_mul_f32 v[208:209], v[0:1], v[32:33]
	v_pk_mul_f32 v[210:211], v[2:3], v[34:35]
	v_pk_fma_f32 v[208:209], v[4:5], v[36:37], v[208:209]
	v_pk_fma_f32 v[210:211], v[6:7], v[38:39], v[210:211]
	v_pk_fma_f32 v[208:209], v[8:9], v[40:41], v[208:209]
	v_pk_fma_f32 v[210:211], v[10:11], v[42:43], v[210:211]
	v_pk_fma_f32 v[208:209], v[12:13], v[44:45], v[208:209]
	v_pk_fma_f32 v[210:211], v[14:15], v[46:47], v[210:211]
	v_pk_fma_f32 v[208:209], v[16:17], v[48:49], v[208:209]
	v_pk_fma_f32 v[210:211], v[18:19], v[50:51], v[210:211]
	v_pk_fma_f32 v[208:209], v[20:21], v[52:53], v[208:209]
	v_pk_fma_f32 v[210:211], v[22:23], v[54:55], v[210:211]
	v_pk_fma_f32 v[208:209], v[24:25], v[56:57], v[208:209]
	v_pk_fma_f32 v[210:211], v[26:27], v[58:59], v[210:211]
	v_pk_fma_f32 v[208:209], v[28:29], v[60:61], v[208:209]
	v_pk_fma_f32 v[210:211], v[30:31], v[62:63], v[210:211]
	v_pk_add_f32 v[208:209], v[208:209], v[210:211]
	v_add_f32_e32 v207, v208, v209
	v_mad_u32_u24 v217, v95, s52, v220
	v_add_u32_e32 v218, v217, v221
	global_load_dwordx4 v[186:189], v217, s[30:31]
	global_load_dwordx2 v[190:191], v218, s[30:31]
	s_mov_b32 s89, s7
	s_mov_b32 s90, s8
	s_mov_b32 s7, s53
	s_mov_b32 s8, s54
	s_add_i32 s53, s7, 1
	s_mov_b32 s54, s8
	s_cmp_eq_u32 s53, 8
	s_cselect_b32 s53, 0, s53
	s_cselect_b32 s34, 1, 0
	s_add_i32 s54, s54, s34
	s_mul_i32 s55, s53, s5
	s_add_i32 s55, s55, s6
	s_min_u32 s55, s55, 0x3fff
	s_and_b32 s34, s54, 7
	s_mul_i32 s34, s34, 0x300000
	s_cmp_lt_u32 s54, 8
	s_cselect_b32 s30, s16, s18
	s_cselect_b32 s31, s17, s19
	s_add_u32 s30, s30, s34
	s_addc_u32 s31, s31, 0
	s_and_b32 s34, s54, 7
	s_lshl_b32 s34, s34, 6
	s_lshl_b32 s35, s55, 12
	s_add_u32 s34, s34, s35
	s_add_u32 s32, s10, s34
	s_addc_u32 s33, s11, 0
	s_lshl_b32 s34, s53, 9
	v_add_u32_e32 v216, s34, v223
	ds_read_b128 v[80:83], v216 offset:0
	ds_read_b128 v[84:87], v216 offset:16
	ds_read_b128 v[88:91], v216 offset:32
	ds_read_b128 v[92:95], v216 offset:48
	v_cndmask_b32_e64 v212, v200, v192, s[44:45]
	v_cndmask_b32_e64 v213, v192, v200, s[44:45]
	v_cndmask_b32_e64 v214, v201, v193, s[44:45]
	v_cndmask_b32_e64 v215, v193, v201, s[44:45]
	v_add_f32_dpp v192, v212, v213 row_half_mirror row_mask:0xf bank_mask:0xf
	v_add_f32_dpp v193, v214, v215 row_half_mirror row_mask:0xf bank_mask:0xf
	v_cndmask_b32_e64 v212, v202, v194, s[44:45]
	v_cndmask_b32_e64 v213, v194, v202, s[44:45]
	v_cndmask_b32_e64 v214, v203, v195, s[44:45]
	v_cndmask_b32_e64 v215, v195, v203, s[44:45]
	v_add_f32_dpp v194, v212, v213 row_half_mirror row_mask:0xf bank_mask:0xf
	v_add_f32_dpp v195, v214, v215 row_half_mirror row_mask:0xf bank_mask:0xf
	v_cndmask_b32_e64 v212, v204, v196, s[44:45]
	v_cndmask_b32_e64 v213, v196, v204, s[44:45]
	v_cndmask_b32_e64 v214, v205, v197, s[44:45]
	v_cndmask_b32_e64 v215, v197, v205, s[44:45]
	v_add_f32_dpp v196, v212, v213 row_half_mirror row_mask:0xf bank_mask:0xf
	v_add_f32_dpp v197, v214, v215 row_half_mirror row_mask:0xf bank_mask:0xf
	v_cndmask_b32_e64 v212, v206, v198, s[44:45]
	v_cndmask_b32_e64 v213, v198, v206, s[44:45]
	v_cndmask_b32_e64 v214, v207, v199, s[44:45]
	v_cndmask_b32_e64 v215, v199, v207, s[44:45]
	v_add_f32_dpp v198, v212, v213 row_half_mirror row_mask:0xf bank_mask:0xf
	v_add_f32_dpp v199, v214, v215 row_half_mirror row_mask:0xf bank_mask:0xf
	v_cndmask_b32_e64 v212, v196, v192, s[42:43]
	v_cndmask_b32_e64 v213, v192, v196, s[42:43]
	v_cndmask_b32_e64 v214, v197, v193, s[42:43]
	v_cndmask_b32_e64 v215, v193, v197, s[42:43]
	v_add_f32_dpp v192, v212, v213 quad_perm:[2,3,0,1] row_mask:0xf bank_mask:0xf
	v_add_f32_dpp v193, v214, v215 quad_perm:[2,3,0,1] row_mask:0xf bank_mask:0xf
	v_cndmask_b32_e64 v212, v198, v194, s[42:43]
	v_cndmask_b32_e64 v213, v194, v198, s[42:43]
	v_cndmask_b32_e64 v214, v199, v195, s[42:43]
	v_cndmask_b32_e64 v215, v195, v199, s[42:43]
	v_add_f32_dpp v194, v212, v213 quad_perm:[2,3,0,1] row_mask:0xf bank_mask:0xf
	v_add_f32_dpp v195, v214, v215 quad_perm:[2,3,0,1] row_mask:0xf bank_mask:0xf
	v_cndmask_b32_e64 v212, v194, v192, s[40:41]
	v_cndmask_b32_e64 v213, v192, v194, s[40:41]
	v_cndmask_b32_e64 v214, v195, v193, s[40:41]
	v_cndmask_b32_e64 v215, v193, v195, s[40:41]
	v_add_f32_dpp v192, v212, v213 quad_perm:[1,0,3,2] row_mask:0xf bank_mask:0xf
	v_add_f32_dpp v193, v214, v215 quad_perm:[1,0,3,2] row_mask:0xf bank_mask:0xf
	s_lshl_b32 s34, s89, 9
	s_addk_i32 s34, 0x1000
	v_add_u32_e32 v219, s34, v222
	s_cmp_eq_u32 s90, 0
	s_cbranch_scc1 .Lex_ufirst
	ds_read_b64 v[212:213], v219
	s_waitcnt lgkmcnt(0)
	v_pk_add_f32 v[192:193], v[192:193], v[212:213]
